# same as previous (last XCD leader releases all XCDs directly) but bumps all 16 possible XGEN words, not only 8 (robust to any XCC id)
# baseline (speedup 1.0000x reference)
; __device__ __forceinline__ unsigned xb_ld(unsigned* p)              { return __hip_atomic_load(p, __ATOMIC_RELAXED, __HIP_MEMORY_SCOPE_AGENT); }
; __device__ __forceinline__ unsigned xb_add(unsigned* p, unsigned v) { return __hip_atomic_fetch_add(p, v, __ATOMIC_RELAXED, __HIP_MEMORY_SCOPE_AGENT); }
; #define XB_SPIN(cond, bar) do { unsigned _sp = 0; while (cond) { __builtin_amdgcn_s_sleep(1); \
;     if ((++_sp & 255u) == 0u) { if (xb_ld(&(bar)[XB_TMO])) break; if (_sp > XB_SPIN_CAP) { atomicAdd(&(bar)[XB_TMO], 1u); break; } } } } while (0)
; __device__ __forceinline__ void xcd_barrier(const XcdBarrier& b) {
;     ...
;             const unsigned og = xb_add(&bar[XB_TOP], 1u);
;             const unsigned tg = og / nx;
;             if (og + 1u == (tg + 1u) * nx) xb_add(&bar[XB_TOPGEN], 1u);
;             else XB_SPIN(xb_ld(&bar[XB_TOPGEN]) == tg, bar);
;             __builtin_amdgcn_fence(__ATOMIC_ACQUIRE, "agent");
;             xb_add(&bar[XB_XGEN(b.x)], 1u);
;             asm volatile("s_waitcnt vmcnt(0)" ::: "memory");
.LBB0_120:
	s_or_b64 exec, exec, s[6:7]
	s_and_saveexec_b64 s[6:7], s[10:11]
	s_cbranch_execz .LBB0_122
	v_mov_b32_e32 v2, 1
	global_atomic_add v[0:1], v2, off
	v_mov_b32_e32 v3, 0xde400
	global_atomic_add v3, v2, s[50:51] offset:0
	global_atomic_add v3, v2, s[50:51] offset:256
	global_atomic_add v3, v2, s[50:51] offset:512
	global_atomic_add v3, v2, s[50:51] offset:768
	global_atomic_add v3, v2, s[50:51] offset:1024
	global_atomic_add v3, v2, s[50:51] offset:1280
	global_atomic_add v3, v2, s[50:51] offset:1536
	global_atomic_add v3, v2, s[50:51] offset:1792
	global_atomic_add v3, v2, s[50:51] offset:2048
	global_atomic_add v3, v2, s[50:51] offset:2304
	global_atomic_add v3, v2, s[50:51] offset:2560
	global_atomic_add v3, v2, s[50:51] offset:2816
	global_atomic_add v3, v2, s[50:51] offset:3072
	global_atomic_add v3, v2, s[50:51] offset:3328
	global_atomic_add v3, v2, s[50:51] offset:3584
	global_atomic_add v3, v2, s[50:51] offset:3840

; __device__ __forceinline__ unsigned xb_ld(unsigned* p)              { return __hip_atomic_load(p, __ATOMIC_RELAXED, __HIP_MEMORY_SCOPE_AGENT); }
; __device__ __forceinline__ unsigned xb_add(unsigned* p, unsigned v) { return __hip_atomic_fetch_add(p, v, __ATOMIC_RELAXED, __HIP_MEMORY_SCOPE_AGENT); }
; #define XB_SPIN(cond, bar) do { unsigned _sp = 0; while (cond) { __builtin_amdgcn_s_sleep(1); \
;     if ((++_sp & 255u) == 0u) { if (xb_ld(&(bar)[XB_TMO])) break; if (_sp > XB_SPIN_CAP) { atomicAdd(&(bar)[XB_TMO], 1u); break; } } } } while (0)
; __device__ __forceinline__ void xcd_barrier(const XcdBarrier& b) {
;     ...
;             const unsigned og = xb_add(&bar[XB_TOP], 1u);
;             const unsigned tg = og / nx;
;             if (og + 1u == (tg + 1u) * nx) xb_add(&bar[XB_TOPGEN], 1u);
;             else XB_SPIN(xb_ld(&bar[XB_TOPGEN]) == tg, bar);
;             __builtin_amdgcn_fence(__ATOMIC_ACQUIRE, "agent");
;             xb_add(&bar[XB_XGEN(b.x)], 1u);
;             asm volatile("s_waitcnt vmcnt(0)" ::: "memory");
.LBB0_250:
	s_or_b64 exec, exec, s[6:7]
	s_and_saveexec_b64 s[6:7], s[8:9]
	s_cbranch_execz .LBB0_252
	global_atomic_add v[0:1], v156, off
	v_readlane_b32 vcc_lo, v253, 63
	v_readlane_b32 vcc_hi, v254, 0
	s_nop 4
	global_atomic_add v97, v156, vcc offset:-4096
	global_atomic_add v97, v156, vcc offset:-3840
	global_atomic_add v97, v156, vcc offset:-3584
	global_atomic_add v97, v156, vcc offset:-3328
	global_atomic_add v97, v156, vcc offset:-3072
	global_atomic_add v97, v156, vcc offset:-2816
	global_atomic_add v97, v156, vcc offset:-2560
	global_atomic_add v97, v156, vcc offset:-2304
	global_atomic_add v97, v156, vcc offset:-2048
	global_atomic_add v97, v156, vcc offset:-1792
	global_atomic_add v97, v156, vcc offset:-1536
	global_atomic_add v97, v156, vcc offset:-1280
	global_atomic_add v97, v156, vcc offset:-1024
	global_atomic_add v97, v156, vcc offset:-768
	global_atomic_add v97, v156, vcc offset:-512
	global_atomic_add v97, v156, vcc offset:-256

; __device__ __forceinline__ unsigned xb_ld(unsigned* p)              { return __hip_atomic_load(p, __ATOMIC_RELAXED, __HIP_MEMORY_SCOPE_AGENT); }
; __device__ __forceinline__ unsigned xb_add(unsigned* p, unsigned v) { return __hip_atomic_fetch_add(p, v, __ATOMIC_RELAXED, __HIP_MEMORY_SCOPE_AGENT); }
; #define XB_SPIN(cond, bar) do { unsigned _sp = 0; while (cond) { __builtin_amdgcn_s_sleep(1); \
;     if ((++_sp & 255u) == 0u) { if (xb_ld(&(bar)[XB_TMO])) break; if (_sp > XB_SPIN_CAP) { atomicAdd(&(bar)[XB_TMO], 1u); break; } } } } while (0)
; __device__ __forceinline__ void xcd_barrier(const XcdBarrier& b) {
;     ...
;             const unsigned og = xb_add(&bar[XB_TOP], 1u);
;             const unsigned tg = og / nx;
;             if (og + 1u == (tg + 1u) * nx) xb_add(&bar[XB_TOPGEN], 1u);
;             else XB_SPIN(xb_ld(&bar[XB_TOPGEN]) == tg, bar);
;             __builtin_amdgcn_fence(__ATOMIC_ACQUIRE, "agent");
;             xb_add(&bar[XB_XGEN(b.x)], 1u);
;             asm volatile("s_waitcnt vmcnt(0)" ::: "memory");
.LBB0_947:
	s_or_b64 exec, exec, s[8:9]
	s_and_saveexec_b64 s[8:9], s[10:11]
	s_cbranch_execz .LBB0_949
	global_atomic_add v[0:1], v156, off
	v_readlane_b32 vcc_lo, v253, 63
	v_readlane_b32 vcc_hi, v254, 0
	s_nop 4
	global_atomic_add v97, v156, vcc offset:-4096
	global_atomic_add v97, v156, vcc offset:-3840
	global_atomic_add v97, v156, vcc offset:-3584
	global_atomic_add v97, v156, vcc offset:-3328
	global_atomic_add v97, v156, vcc offset:-3072
	global_atomic_add v97, v156, vcc offset:-2816
	global_atomic_add v97, v156, vcc offset:-2560
	global_atomic_add v97, v156, vcc offset:-2304
	global_atomic_add v97, v156, vcc offset:-2048
	global_atomic_add v97, v156, vcc offset:-1792
	global_atomic_add v97, v156, vcc offset:-1536
	global_atomic_add v97, v156, vcc offset:-1280
	global_atomic_add v97, v156, vcc offset:-1024
	global_atomic_add v97, v156, vcc offset:-768
	global_atomic_add v97, v156, vcc offset:-512
	global_atomic_add v97, v156, vcc offset:-256

; __device__ __forceinline__ unsigned xb_ld(unsigned* p)              { return __hip_atomic_load(p, __ATOMIC_RELAXED, __HIP_MEMORY_SCOPE_AGENT); }
; __device__ __forceinline__ unsigned xb_add(unsigned* p, unsigned v) { return __hip_atomic_fetch_add(p, v, __ATOMIC_RELAXED, __HIP_MEMORY_SCOPE_AGENT); }
; #define XB_SPIN(cond, bar) do { unsigned _sp = 0; while (cond) { __builtin_amdgcn_s_sleep(1); \
;     if ((++_sp & 255u) == 0u) { if (xb_ld(&(bar)[XB_TMO])) break; if (_sp > XB_SPIN_CAP) { atomicAdd(&(bar)[XB_TMO], 1u); break; } } } } while (0)
; __device__ __forceinline__ void xcd_barrier(const XcdBarrier& b) {
;     ...
;             const unsigned og = xb_add(&bar[XB_TOP], 1u);
;             const unsigned tg = og / nx;
;             if (og + 1u == (tg + 1u) * nx) xb_add(&bar[XB_TOPGEN], 1u);
;             else XB_SPIN(xb_ld(&bar[XB_TOPGEN]) == tg, bar);
;             __builtin_amdgcn_fence(__ATOMIC_ACQUIRE, "agent");
;             xb_add(&bar[XB_XGEN(b.x)], 1u);
;             asm volatile("s_waitcnt vmcnt(0)" ::: "memory");
.LBB0_1118:
	s_or_b64 exec, exec, s[8:9]
	s_and_saveexec_b64 s[8:9], s[12:13]
	s_cbranch_execz .LBB0_1120
	global_atomic_add v[0:1], v156, off
	v_readlane_b32 vcc_lo, v253, 63
	v_readlane_b32 vcc_hi, v254, 0
	s_nop 4
	global_atomic_add v97, v156, vcc offset:-4096
	global_atomic_add v97, v156, vcc offset:-3840
	global_atomic_add v97, v156, vcc offset:-3584
	global_atomic_add v97, v156, vcc offset:-3328
	global_atomic_add v97, v156, vcc offset:-3072
	global_atomic_add v97, v156, vcc offset:-2816
	global_atomic_add v97, v156, vcc offset:-2560
	global_atomic_add v97, v156, vcc offset:-2304
	global_atomic_add v97, v156, vcc offset:-2048
	global_atomic_add v97, v156, vcc offset:-1792
	global_atomic_add v97, v156, vcc offset:-1536
	global_atomic_add v97, v156, vcc offset:-1280
	global_atomic_add v97, v156, vcc offset:-1024
	global_atomic_add v97, v156, vcc offset:-768
	global_atomic_add v97, v156, vcc offset:-512
	global_atomic_add v97, v156, vcc offset:-256
